# k15 + group barrier: consistency-word load overlapped with the arrival atomic, last arriver skips the spin
# baseline (speedup 1.0000x reference)
; __device__ __forceinline__ unsigned xb_ld(unsigned* p)              { return __hip_atomic_load(p, __ATOMIC_RELAXED, __HIP_MEMORY_SCOPE_AGENT); }
; __device__ __forceinline__ unsigned xb_add(unsigned* p, unsigned v) { return __hip_atomic_fetch_add(p, v, __ATOMIC_RELAXED, __HIP_MEMORY_SCOPE_AGENT); }
; #define XB_SPIN(cond, bar) do { unsigned _sp = 0; while (cond) { __builtin_amdgcn_s_sleep(1); \
;     if ((++_sp & 255u) == 0u) { if (xb_ld(&(bar)[XB_TMO])) break; if (_sp > XB_SPIN_CAP) { atomicAdd(&(bar)[XB_TMO], 1u); break; } } } } while (0)
; __device__ __forceinline__ void xcd_barrier(const XcdBarrier& b) {
;     asm volatile("s_waitcnt vmcnt(0)" ::: "memory");
;     __syncthreads();
;     if (threadIdx.x == 0) {
;         unsigned* bar = b.bar;
;         __builtin_amdgcn_s_waitcnt(0);
;         unsigned nloc = b.st[0], nx = b.st[1];
;         if (nloc == 0u) { xcd_barrier_complete(bar, b.x, nloc, nx); b.st[0] = nloc; b.st[1] = nx; }
;         const unsigned old = xb_add(&bar[XB_XSUB(b.x)], 1u);
;         const unsigned gen = old / nloc;
;         if (old + 1u == (gen + 1u) * nloc) {
;             __builtin_amdgcn_fence(__ATOMIC_RELEASE, "agent");
;             asm volatile("s_waitcnt vmcnt(0)" ::: "memory");
;             const unsigned og = xb_add(&bar[XB_TOP], 1u);
;             const unsigned tg = og / nx;
;             if (og + 1u == (tg + 1u) * nx) xb_add(&bar[XB_TOPGEN], 1u);
;             else XB_SPIN(xb_ld(&bar[XB_TOPGEN]) == tg, bar);
;             __builtin_amdgcn_fence(__ATOMIC_ACQUIRE, "agent");
;             xb_add(&bar[XB_XGEN(b.x)], 1u);
;             asm volatile("s_waitcnt vmcnt(0)" ::: "memory");
;         } else {
;             XB_SPIN(xb_ld(&bar[XB_XGEN(b.x)]) == gen, bar);
;             __builtin_amdgcn_fence(__ATOMIC_ACQUIRE, "agent");
;             asm volatile("s_waitcnt vmcnt(0)" ::: "memory");
;         }
;     }
;     __syncthreads();
; }
.LBB0_1655:
	v_readlane_b32 s4, v253, 0
	s_mov_b32 s5, 0x6c19b06
	s_cmpk_lg_u32 s4, 0x100
	s_cbranch_scc1 .Lgb_normal
	s_bitcmp1_b32 s5, s22
	s_cbranch_scc0 .Lgb_normal
	v_readlane_b32 s6, v253, 6
	v_readlane_b32 s7, v253, 7
	v_readlane_b32 s8, v254, 18
	s_and_b32 s9, s8, 7
	s_lshl_b32 s9, s9, 2
	v_mov_b32_e32 v4, s9
	s_and_b32 s8, s8, 63
	s_lshl_b32 s8, s8, 5
	s_addk_i32 s8, 0x3400
	v_mov_b32_e32 v1, s8
	v_mov_b32_e32 v2, 1
	global_load_dword v0, v4, s[6:7] offset:-508 sc1
	global_atomic_add v3, v1, v2, s[6:7] sc0
	s_waitcnt vmcnt(0)
	v_readfirstlane_b32 s9, v0
	s_cmp_eq_u32 s9, 0
	s_cbranch_scc1 .Lgb_normal
	s_add_i32 s10, s9, -1
	s_and_b32 s10, s10, s9
	s_cmp_lg_u32 s10, 0
	s_cbranch_scc1 .Lgb_normal
	v_readfirstlane_b32 s9, v3
	s_and_b32 s10, s9, 3
	s_cmp_eq_u32 s10, 3
	s_cbranch_scc1 .Lgb_done
	s_andn2_b32 s9, s9, 3
	s_add_i32 s9, s9, 4
	s_mov_b32 s11, 0
